# speedup vs baseline: 1.0051x; 1.0006x over previous
; #define STAGE(P, BASE, br, kt) do { const u16* _gb = (BASE) + ((size_t)(br) * K + (size_t)(kt) * BK); \
;     __builtin_amdgcn_global_load_lds((const unsigned*)(_gb + goff0), (unsigned*)((char*)(P) + tid * 16), 16, 0, 0); \
;     __builtin_amdgcn_global_load_lds((const unsigned*)(_gb + (size_t)64 * K + goff0), (unsigned*)((char*)(P) + tid * 16 + 8192), 16, 0, 0); } while (0)
; #define LDA(dst, b, h) _Pragma("unroll") for (int m = 0; m < 4; ++m) _Pragma("unroll") for (int k = 0; k < 2; ++k) \
;     dst[m][k] = *reinterpret_cast<const bf16x8*>((char*)SA(b, h) + lds_byte(wr * 64 + m * 16 + fr, k * 32 + fq * 8))
; #define LDB(dst, b, h) _Pragma("unroll") for (int n = 0; n < 2; ++n) _Pragma("unroll") for (int k = 0; k < 2; ++k) \
;     dst[n][k] = *reinterpret_cast<const bf16x8*>((char*)SB(b, h) + lds_byte(wc * 32 + n * 16 + fr, k * 32 + fq * 8))
; #define MMA(ai, bj, At, Bt_) do { __builtin_amdgcn_s_setprio(1); \
;     _Pragma("unroll") for (int m = 0; m < 4; ++m) _Pragma("unroll") for (int n = 0; n < 2; ++n) _Pragma("unroll") for (int k = 0; k < 2; ++k) \
;       acc[ai][bj][m][n] = __builtin_amdgcn_mfma_f32_16x16x32_bf16(Bt_[n][k], At[m][k], acc[ai][bj][m][n], 0, 0, 0); \
;     __builtin_amdgcn_s_setprio(0); } while (0)
; #define WAIT_V(n) asm volatile("s_waitcnt vmcnt(" #n ")" ::: "memory")
; #define WAIT_L(n) asm volatile("s_waitcnt lgkmcnt(" #n ")" ::: "memory")
; __device__ __forceinline__ void gemm_phase(KP p, char* shmc, const u16* __restrict__ A,
;                                            const u16* __restrict__ Bt, const int N, const int K, const int mode,
;                                            const float* __restrict__ xin, const float resw) {
;     ...
;     WAIT_V(0);
;     if (wr == 1) BAR;
;     BAR;
;     for (int t = 0; t < nt - 2; t += 2) {
;       LDB(B0, 0, 0); SCHED; LDA(At, 0, 0); STAGE(SA(1, 1), A, brow + HALF, t + 1);
;       WAIT_L(8); BAR; WAIT_L(0); MMA(0, 0, At, B0); BAR; SCHED;
;       LDB(B1, 0, 1); STAGE(SB(0, 0), Bt, bcol, t + 2);
;       BAR; WAIT_L(0); MMA(0, 1, At, B1); BAR;
;       LDA(At, 0, 1); STAGE(SA(0, 0), A, brow, t + 2);
;       BAR; WAIT_L(0); MMA(1, 0, At, B0); BAR; SCHED;
;       STAGE(SB(0, 1), Bt, bcol + HALF, t + 2);
;       WAIT_V(6); BAR; MMA(1, 1, At, B1); BAR;
;       LDB(B0, 1, 0); SCHED; LDA(At, 1, 0); STAGE(SA(0, 1), A, brow + HALF, t + 2);
;       WAIT_L(8); BAR; WAIT_L(0); MMA(0, 0, At, B0); BAR; SCHED;
.Lmy_noextra:
	s_add_u32 s8, s8, 0x80
	s_addc_u32 s9, s9, 0
	s_add_u32 s36, s36, 0x100
	s_addc_u32 s37, s37, 0
	s_add_u32 s26, s26, 0x100
	s_addc_u32 s27, s27, 0
	s_add_u32 s38, s38, 0x100
	s_addc_u32 s39, s39, 0
	s_barrier
	ds_read_b128 v[194:197], v235 offset:0
	ds_read_b128 v[198:201], v235 offset:1024
	ds_read_b128 v[202:205], v235 offset:2048
	ds_read_b128 v[206:209], v235 offset:3072
	ds_read_b128 v[128:131], v234 offset:0
	ds_read_b128 v[132:135], v234 offset:1024
	ds_read_b128 v[136:139], v234 offset:2048
	ds_read_b128 v[140:143], v234 offset:3072
	ds_read_b128 v[144:147], v234 offset:4096
	ds_read_b128 v[148:151], v234 offset:5120
	ds_read_b128 v[152:155], v234 offset:6144
	ds_read_b128 v[156:159], v234 offset:7168
	s_cmp_lg_u32 s49, 2
	s_cbranch_scc1 .Lmy_entry_n
	s_sub_i32 s42, s73, 8
	s_cmp_lt_u32 s42, 4
	s_cbranch_scc1 .Lmy_entry_sw
.Lmy_entry_n:
	s_waitcnt vmcnt(12) lgkmcnt(0)
	s_barrier
	v_mfma_f32_16x16x32_bf16 v[120:123], v[194:197], v[128:131], 0
	v_mfma_f32_16x16x32_bf16 v[112:115], v[202:205], v[128:131], 0
	ds_read_b128 v[218:221], v235 offset:16384
	v_mfma_f32_16x16x32_bf16 v[104:107], v[194:197], v[136:139], 0
	ds_read_b128 v[222:225], v235 offset:17408
	s_add_u32 m0, s40, 0x0
	v_mfma_f32_16x16x32_bf16 v[96:99], v[202:205], v[136:139], 0
	ds_read_b128 v[226:229], v235 offset:18432
	global_load_lds_dwordx4 v236, s[36:37]
	v_mfma_f32_16x16x32_bf16 v[88:91], v[194:197], v[144:147], 0
	ds_read_b128 v[230:233], v235 offset:19456
	s_add_u32 m0, s40, 0x2000
	v_mfma_f32_16x16x32_bf16 v[80:83], v[202:205], v[144:147], 0
	global_load_lds_dwordx4 v237, s[36:37]
	v_mfma_f32_16x16x32_bf16 v[72:75], v[194:197], v[152:155], 0
	s_add_u32 s36, s36, 0x80
	s_addc_u32 s37, s37, 0
	v_mfma_f32_16x16x32_bf16 v[64:67], v[202:205], v[152:155], 0
	s_add_u32 m0, s40, 0x10000
	v_mfma_f32_16x16x32_bf16 v[120:123], v[198:201], v[132:135], v[120:123]
	global_load_lds_dwordx4 v236, s[26:27]
	v_mfma_f32_16x16x32_bf16 v[112:115], v[206:209], v[132:135], v[112:115]
	s_add_u32 m0, s40, 0x12000
	v_mfma_f32_16x16x32_bf16 v[104:107], v[198:201], v[140:143], v[104:107]
	global_load_lds_dwordx4 v237, s[26:27]
	v_mfma_f32_16x16x32_bf16 v[96:99], v[206:209], v[140:143], v[96:99]
	s_add_u32 s26, s26, 0x80
	s_addc_u32 s27, s27, 0
	v_mfma_f32_16x16x32_bf16 v[88:91], v[198:201], v[148:151], v[88:91]
	v_mfma_f32_16x16x32_bf16 v[80:83], v[206:209], v[148:151], v[80:83]
	v_mfma_f32_16x16x32_bf16 v[72:75], v[198:201], v[156:159], v[72:75]
	v_mfma_f32_16x16x32_bf16 v[64:67], v[206:209], v[156:159], v[64:67]
	s_waitcnt vmcnt(12) lgkmcnt(0)
	s_barrier
	v_mfma_f32_16x16x32_bf16 v[124:127], v[218:221], v[128:131], 0
	v_mfma_f32_16x16x32_bf16 v[116:119], v[226:229], v[128:131], 0
	ds_read_b128 v[160:163], v234 offset:16384
	v_mfma_f32_16x16x32_bf16 v[108:111], v[218:221], v[136:139], 0
	ds_read_b128 v[164:167], v234 offset:17408
	v_mfma_f32_16x16x32_bf16 v[100:103], v[226:229], v[136:139], 0
	ds_read_b128 v[168:171], v234 offset:18432
	s_add_u32 m0, s40, 0x14000
	v_mfma_f32_16x16x32_bf16 v[92:95], v[218:221], v[144:147], 0
	ds_read_b128 v[172:175], v234 offset:19456
	v_mfma_f32_16x16x32_bf16 v[84:87], v[226:229], v[144:147], 0
	ds_read_b128 v[176:179], v234 offset:20480
	global_load_lds_dwordx4 v236, s[38:39]
	v_mfma_f32_16x16x32_bf16 v[76:79], v[218:221], v[152:155], 0
	ds_read_b128 v[180:183], v234 offset:21504
	v_mfma_f32_16x16x32_bf16 v[68:71], v[226:229], v[152:155], 0
	ds_read_b128 v[184:187], v234 offset:22528
	s_add_u32 m0, s40, 0x16000
	v_mfma_f32_16x16x32_bf16 v[124:127], v[222:225], v[132:135], v[124:127]
	ds_read_b128 v[188:191], v234 offset:23552
	v_mfma_f32_16x16x32_bf16 v[116:119], v[230:233], v[132:135], v[116:119]
	global_load_lds_dwordx4 v237, s[38:39]
	v_mfma_f32_16x16x32_bf16 v[108:111], v[222:225], v[140:143], v[108:111]
	v_mfma_f32_16x16x32_bf16 v[100:103], v[230:233], v[140:143], v[100:103]
	s_add_u32 s38, s38, 0x80
	s_addc_u32 s39, s39, 0
	v_mfma_f32_16x16x32_bf16 v[92:95], v[222:225], v[148:151], v[92:95]
	v_mfma_f32_16x16x32_bf16 v[84:87], v[230:233], v[148:151], v[84:87]
	v_mfma_f32_16x16x32_bf16 v[76:79], v[222:225], v[156:159], v[76:79]
	v_mfma_f32_16x16x32_bf16 v[68:71], v[230:233], v[156:159], v[68:71]
	s_waitcnt vmcnt(12) lgkmcnt(0)
	s_barrier
	v_mfma_f32_16x16x32_bf16 v[56:59], v[194:197], v[160:163], 0
	v_mfma_f32_16x16x32_bf16 v[48:51], v[202:205], v[160:163], 0
	ds_read_b128 v[128:131], v234 offset:32768
	v_mfma_f32_16x16x32_bf16 v[40:43], v[194:197], v[168:171], 0
	ds_read_b128 v[132:135], v234 offset:33792
	v_mfma_f32_16x16x32_bf16 v[32:35], v[202:205], v[168:171], 0
	ds_read_b128 v[136:139], v234 offset:34816
	s_add_u32 m0, s40, 0x4000
	v_mfma_f32_16x16x32_bf16 v[24:27], v[194:197], v[176:179], 0
	ds_read_b128 v[140:143], v234 offset:35840
	v_mfma_f32_16x16x32_bf16 v[16:19], v[202:205], v[176:179], 0
	ds_read_b128 v[144:147], v234 offset:36864
	global_load_lds_dwordx4 v236, s[8:9]
	v_mfma_f32_16x16x32_bf16 v[8:11], v[194:197], v[184:187], 0
	ds_read_b128 v[148:151], v234 offset:37888
	v_mfma_f32_16x16x32_bf16 v[0:3], v[202:205], v[184:187], 0
	ds_read_b128 v[152:155], v234 offset:38912
	s_add_u32 m0, s40, 0x6000
	v_mfma_f32_16x16x32_bf16 v[56:59], v[198:201], v[164:167], v[56:59]
	ds_read_b128 v[156:159], v234 offset:39936
	v_mfma_f32_16x16x32_bf16 v[48:51], v[206:209], v[164:167], v[48:51]
	global_load_lds_dwordx4 v237, s[8:9]
	v_mfma_f32_16x16x32_bf16 v[40:43], v[198:201], v[172:175], v[40:43]
	v_mfma_f32_16x16x32_bf16 v[32:35], v[206:209], v[172:175], v[32:35]
	s_add_u32 s8, s8, 0x80
	s_addc_u32 s9, s9, 0
	v_mfma_f32_16x16x32_bf16 v[24:27], v[198:201], v[180:183], v[24:27]
	v_mfma_f32_16x16x32_bf16 v[16:19], v[206:209], v[180:183], v[16:19]
	v_mfma_f32_16x16x32_bf16 v[8:11], v[198:201], v[188:191], v[8:11]
	v_mfma_f32_16x16x32_bf16 v[0:3], v[206:209], v[188:191], v[0:3]
	s_waitcnt vmcnt(12) lgkmcnt(0)
	s_barrier
; #define STAGE(P, BASE, br, kt) do { const u16* _gb = (BASE) + ((size_t)(br) * K + (size_t)(kt) * BK); \
;     __builtin_amdgcn_global_load_lds((const unsigned*)(_gb + goff0), (unsigned*)((char*)(P) + tid * 16), 16, 0, 0); \
;     __builtin_amdgcn_global_load_lds((const unsigned*)(_gb + (size_t)64 * K + goff0), (unsigned*)((char*)(P) + tid * 16 + 8192), 16, 0, 0); } while (0)
; #define LDA(dst, b, h) _Pragma("unroll") for (int m = 0; m < 4; ++m) _Pragma("unroll") for (int k = 0; k < 2; ++k) \
;     dst[m][k] = *reinterpret_cast<const bf16x8*>((char*)SA(b, h) + lds_byte(wr * 64 + m * 16 + fr, k * 32 + fq * 8))
; #define LDB(dst, b, h) _Pragma("unroll") for (int n = 0; n < 2; ++n) _Pragma("unroll") for (int k = 0; k < 2; ++k) \
;     dst[n][k] = *reinterpret_cast<const bf16x8*>((char*)SB(b, h) + lds_byte(wc * 32 + n * 16 + fr, k * 32 + fq * 8))
; #define WAIT_V(n) asm volatile("s_waitcnt vmcnt(" #n ")" ::: "memory")
; #define WAIT_L(n) asm volatile("s_waitcnt lgkmcnt(" #n ")" ::: "memory")
; #define BAR __builtin_amdgcn_s_barrier()
; #define SCHED __builtin_amdgcn_sched_barrier(0)
; __device__ __forceinline__ void gemm_phase(KP p, char* shmc, const u16* __restrict__ A,
;                                            const u16* __restrict__ Bt, const int N, const int K, const int mode,
;                                            const float* __restrict__ xin, const float resw) {
;     ...
;     for (int t = 0; t < nt - 2; t += 2) {
;       LDB(B0, 0, 0); SCHED; LDA(At, 0, 0); STAGE(SA(1, 1), A, brow + HALF, t + 1);
;       WAIT_L(8); BAR; WAIT_L(0); MMA(0, 0, At, B0); BAR; SCHED;
;       LDB(B1, 0, 1); STAGE(SB(0, 0), Bt, bcol, t + 2);
;       BAR; WAIT_L(0); MMA(0, 1, At, B1); BAR;
;       LDA(At, 0, 1); STAGE(SA(0, 0), A, brow, t + 2);
;       BAR; WAIT_L(0); MMA(1, 0, At, B0); BAR; SCHED;
;       STAGE(SB(0, 1), Bt, bcol + HALF, t + 2);
;       WAIT_V(6); BAR; MMA(1, 1, At, B1); BAR;
;       LDB(B0, 1, 0); SCHED; LDA(At, 1, 0); STAGE(SA(0, 1), A, brow + HALF, t + 2);
;       WAIT_L(8); BAR; WAIT_L(0); MMA(0, 0, At, B0); BAR; SCHED;
;       LDB(B1, 1, 1); STAGE(SB(1, 0), Bt, bcol, t + 3);
;       BAR; WAIT_L(0); MMA(0, 1, At, B1); BAR;
;       LDA(At, 1, 1); STAGE(SA(1, 0), A, brow, t + 3);
;       BAR; WAIT_L(0); MMA(1, 0, At, B0); BAR; SCHED;
;       STAGE(SB(1, 1), Bt, bcol + HALF, t + 3);
;       WAIT_V(6); BAR; MMA(1, 1, At, B1); BAR;
;     }
	v_mfma_f32_16x16x32_bf16 v[60:63], v[218:221], v[160:163], 0
	v_mfma_f32_16x16x32_bf16 v[52:55], v[226:229], v[160:163], 0
	ds_read_b128 v[194:197], v235 offset:32768
	v_mfma_f32_16x16x32_bf16 v[44:47], v[218:221], v[168:171], 0
	ds_read_b128 v[198:201], v235 offset:33792
	v_mfma_f32_16x16x32_bf16 v[36:39], v[226:229], v[168:171], 0
	ds_read_b128 v[202:205], v235 offset:34816
	s_add_u32 m0, s40, 0x8000
	v_mfma_f32_16x16x32_bf16 v[28:31], v[218:221], v[176:179], 0
	ds_read_b128 v[206:209], v235 offset:35840
	v_mfma_f32_16x16x32_bf16 v[20:23], v[226:229], v[176:179], 0
	global_load_lds_dwordx4 v236, s[36:37]
	v_mfma_f32_16x16x32_bf16 v[12:15], v[218:221], v[184:187], 0
	v_mfma_f32_16x16x32_bf16 v[4:7], v[226:229], v[184:187], 0
	s_add_u32 m0, s40, 0xa000
	v_mfma_f32_16x16x32_bf16 v[60:63], v[222:225], v[164:167], v[60:63]
	v_mfma_f32_16x16x32_bf16 v[52:55], v[230:233], v[164:167], v[52:55]
	global_load_lds_dwordx4 v237, s[36:37]
	v_mfma_f32_16x16x32_bf16 v[44:47], v[222:225], v[172:175], v[44:47]
	v_mfma_f32_16x16x32_bf16 v[36:39], v[230:233], v[172:175], v[36:39]
	s_add_u32 s36, s36, 0x80
	s_addc_u32 s37, s37, 0
	v_mfma_f32_16x16x32_bf16 v[28:31], v[222:225], v[180:183], v[28:31]
	v_mfma_f32_16x16x32_bf16 v[20:23], v[230:233], v[180:183], v[20:23]
	v_mfma_f32_16x16x32_bf16 v[12:15], v[222:225], v[188:191], v[12:15]
	v_mfma_f32_16x16x32_bf16 v[4:7], v[230:233], v[188:191], v[4:7]
	s_waitcnt vmcnt(12) lgkmcnt(0)
	s_barrier
	v_mfma_f32_16x16x32_bf16 v[120:123], v[194:197], v[128:131], v[120:123]
	v_mfma_f32_16x16x32_bf16 v[112:115], v[202:205], v[128:131], v[112:115]
	ds_read_b128 v[218:221], v235 offset:49152
	v_mfma_f32_16x16x32_bf16 v[104:107], v[194:197], v[136:139], v[104:107]
	ds_read_b128 v[222:225], v235 offset:50176
	v_mfma_f32_16x16x32_bf16 v[96:99], v[202:205], v[136:139], v[96:99]
	ds_read_b128 v[226:229], v235 offset:51200
	s_add_u32 m0, s40, 0x18000
	v_mfma_f32_16x16x32_bf16 v[88:91], v[194:197], v[144:147], v[88:91]
	ds_read_b128 v[230:233], v235 offset:52224
	v_mfma_f32_16x16x32_bf16 v[80:83], v[202:205], v[144:147], v[80:83]
	global_load_lds_dwordx4 v236, s[26:27]
	v_mfma_f32_16x16x32_bf16 v[72:75], v[194:197], v[152:155], v[72:75]
	v_mfma_f32_16x16x32_bf16 v[64:67], v[202:205], v[152:155], v[64:67]
	s_add_u32 m0, s40, 0x1a000
	v_mfma_f32_16x16x32_bf16 v[120:123], v[198:201], v[132:135], v[120:123]
	v_mfma_f32_16x16x32_bf16 v[112:115], v[206:209], v[132:135], v[112:115]
	global_load_lds_dwordx4 v237, s[26:27]
	v_mfma_f32_16x16x32_bf16 v[104:107], v[198:201], v[140:143], v[104:107]
	v_mfma_f32_16x16x32_bf16 v[96:99], v[206:209], v[140:143], v[96:99]
	s_add_u32 s26, s26, 0x80
	s_addc_u32 s27, s27, 0
	v_mfma_f32_16x16x32_bf16 v[88:91], v[198:201], v[148:151], v[88:91]
	v_mfma_f32_16x16x32_bf16 v[80:83], v[206:209], v[148:151], v[80:83]
	v_mfma_f32_16x16x32_bf16 v[72:75], v[198:201], v[156:159], v[72:75]
	v_mfma_f32_16x16x32_bf16 v[64:67], v[206:209], v[156:159], v[64:67]
	s_waitcnt vmcnt(12) lgkmcnt(0)
	s_barrier
	v_mfma_f32_16x16x32_bf16 v[124:127], v[218:221], v[128:131], v[124:127]
	v_mfma_f32_16x16x32_bf16 v[116:119], v[226:229], v[128:131], v[116:119]
	ds_read_b128 v[160:163], v234 offset:49152
	v_mfma_f32_16x16x32_bf16 v[108:111], v[218:221], v[136:139], v[108:111]
	ds_read_b128 v[164:167], v234 offset:50176
	v_mfma_f32_16x16x32_bf16 v[100:103], v[226:229], v[136:139], v[100:103]
	ds_read_b128 v[168:171], v234 offset:51200
	s_add_u32 m0, s40, 0x1c000
	v_mfma_f32_16x16x32_bf16 v[92:95], v[218:221], v[144:147], v[92:95]
	ds_read_b128 v[172:175], v234 offset:52224
	v_mfma_f32_16x16x32_bf16 v[84:87], v[226:229], v[144:147], v[84:87]
	ds_read_b128 v[176:179], v234 offset:53248
	global_load_lds_dwordx4 v236, s[38:39]
	v_mfma_f32_16x16x32_bf16 v[76:79], v[218:221], v[152:155], v[76:79]
	ds_read_b128 v[180:183], v234 offset:54272
	v_mfma_f32_16x16x32_bf16 v[68:71], v[226:229], v[152:155], v[68:71]
	ds_read_b128 v[184:187], v234 offset:55296
	s_add_u32 m0, s40, 0x1e000
	v_mfma_f32_16x16x32_bf16 v[124:127], v[222:225], v[132:135], v[124:127]
	ds_read_b128 v[188:191], v234 offset:56320
	v_mfma_f32_16x16x32_bf16 v[116:119], v[230:233], v[132:135], v[116:119]
	global_load_lds_dwordx4 v237, s[38:39]
	v_mfma_f32_16x16x32_bf16 v[108:111], v[222:225], v[140:143], v[108:111]
	v_mfma_f32_16x16x32_bf16 v[100:103], v[230:233], v[140:143], v[100:103]
	s_add_u32 s38, s38, 0x80
	s_addc_u32 s39, s39, 0
	v_mfma_f32_16x16x32_bf16 v[92:95], v[222:225], v[148:151], v[92:95]
	v_mfma_f32_16x16x32_bf16 v[84:87], v[230:233], v[148:151], v[84:87]
	v_mfma_f32_16x16x32_bf16 v[76:79], v[222:225], v[156:159], v[76:79]
	v_mfma_f32_16x16x32_bf16 v[68:71], v[230:233], v[156:159], v[68:71]
	s_waitcnt vmcnt(12) lgkmcnt(0)
	s_barrier
; #define STAGE(P, BASE, br, kt) do { const u16* _gb = (BASE) + ((size_t)(br) * K + (size_t)(kt) * BK); \
;     __builtin_amdgcn_global_load_lds((const unsigned*)(_gb + goff0), (unsigned*)((char*)(P) + tid * 16), 16, 0, 0); \
;     __builtin_amdgcn_global_load_lds((const unsigned*)(_gb + (size_t)64 * K + goff0), (unsigned*)((char*)(P) + tid * 16 + 8192), 16, 0, 0); } while (0)
; #define LDA(dst, b, h) _Pragma("unroll") for (int m = 0; m < 4; ++m) _Pragma("unroll") for (int k = 0; k < 2; ++k) \
;     dst[m][k] = *reinterpret_cast<const bf16x8*>((char*)SA(b, h) + lds_byte(wr * 64 + m * 16 + fr, k * 32 + fq * 8))
; #define LDB(dst, b, h) _Pragma("unroll") for (int n = 0; n < 2; ++n) _Pragma("unroll") for (int k = 0; k < 2; ++k) \
;     dst[n][k] = *reinterpret_cast<const bf16x8*>((char*)SB(b, h) + lds_byte(wc * 32 + n * 16 + fr, k * 32 + fq * 8))
; #define WAIT_V(n) asm volatile("s_waitcnt vmcnt(" #n ")" ::: "memory")
; #define WAIT_L(n) asm volatile("s_waitcnt lgkmcnt(" #n ")" ::: "memory")
; #define BAR __builtin_amdgcn_s_barrier()
; #define SCHED __builtin_amdgcn_sched_barrier(0)
; __device__ __forceinline__ void gemm_phase(KP p, char* shmc, const u16* __restrict__ A,
;                                            const u16* __restrict__ Bt, const int N, const int K, const int mode,
;                                            const float* __restrict__ xin, const float resw) {
;     ...
;     for (int t = 0; t < nt - 2; t += 2) {
;       LDB(B0, 0, 0); SCHED; LDA(At, 0, 0); STAGE(SA(1, 1), A, brow + HALF, t + 1);
;       WAIT_L(8); BAR; WAIT_L(0); MMA(0, 0, At, B0); BAR; SCHED;
;       LDB(B1, 0, 1); STAGE(SB(0, 0), Bt, bcol, t + 2);
;       BAR; WAIT_L(0); MMA(0, 1, At, B1); BAR;
;       LDA(At, 0, 1); STAGE(SA(0, 0), A, brow, t + 2);
;       BAR; WAIT_L(0); MMA(1, 0, At, B0); BAR; SCHED;
;       STAGE(SB(0, 1), Bt, bcol + HALF, t + 2);
;       WAIT_V(6); BAR; MMA(1, 1, At, B1); BAR;
;       LDB(B0, 1, 0); SCHED; LDA(At, 1, 0); STAGE(SA(0, 1), A, brow + HALF, t + 2);
;       WAIT_L(8); BAR; WAIT_L(0); MMA(0, 0, At, B0); BAR; SCHED;
;       LDB(B1, 1, 1); STAGE(SB(1, 0), Bt, bcol, t + 3);
;       BAR; WAIT_L(0); MMA(0, 1, At, B1); BAR;
;       LDA(At, 1, 1); STAGE(SA(1, 0), A, brow, t + 3);
;       BAR; WAIT_L(0); MMA(1, 0, At, B0); BAR; SCHED;
;       STAGE(SB(1, 1), Bt, bcol + HALF, t + 3);
;       WAIT_V(6); BAR; MMA(1, 1, At, B1); BAR;
;     }
	v_mfma_f32_16x16x32_bf16 v[56:59], v[194:197], v[160:163], v[56:59]
	v_mfma_f32_16x16x32_bf16 v[48:51], v[202:205], v[160:163], v[48:51]
	ds_read_b128 v[128:131], v234 offset:0
	v_mfma_f32_16x16x32_bf16 v[40:43], v[194:197], v[168:171], v[40:43]
	ds_read_b128 v[132:135], v234 offset:1024
	v_mfma_f32_16x16x32_bf16 v[32:35], v[202:205], v[168:171], v[32:35]
	ds_read_b128 v[136:139], v234 offset:2048
	s_add_u32 m0, s40, 0xc000
	v_mfma_f32_16x16x32_bf16 v[24:27], v[194:197], v[176:179], v[24:27]
	ds_read_b128 v[140:143], v234 offset:3072
	v_mfma_f32_16x16x32_bf16 v[16:19], v[202:205], v[176:179], v[16:19]
	ds_read_b128 v[144:147], v234 offset:4096
	global_load_lds_dwordx4 v236, s[8:9]
	v_mfma_f32_16x16x32_bf16 v[8:11], v[194:197], v[184:187], v[8:11]
	ds_read_b128 v[148:151], v234 offset:5120
	v_mfma_f32_16x16x32_bf16 v[0:3], v[202:205], v[184:187], v[0:3]
	ds_read_b128 v[152:155], v234 offset:6144
	s_add_u32 m0, s40, 0xe000
	v_mfma_f32_16x16x32_bf16 v[56:59], v[198:201], v[164:167], v[56:59]
	ds_read_b128 v[156:159], v234 offset:7168
	v_mfma_f32_16x16x32_bf16 v[48:51], v[206:209], v[164:167], v[48:51]
	global_load_lds_dwordx4 v237, s[8:9]
	v_mfma_f32_16x16x32_bf16 v[40:43], v[198:201], v[172:175], v[40:43]
	v_mfma_f32_16x16x32_bf16 v[32:35], v[206:209], v[172:175], v[32:35]
	s_add_u32 s8, s8, 0x80
	s_addc_u32 s9, s9, 0
	v_mfma_f32_16x16x32_bf16 v[24:27], v[198:201], v[180:183], v[24:27]
	v_mfma_f32_16x16x32_bf16 v[16:19], v[206:209], v[180:183], v[16:19]
	v_mfma_f32_16x16x32_bf16 v[8:11], v[198:201], v[188:191], v[8:11]
	v_mfma_f32_16x16x32_bf16 v[0:3], v[206:209], v[188:191], v[0:3]
	s_waitcnt vmcnt(12) lgkmcnt(0)
	s_barrier
	v_mfma_f32_16x16x32_bf16 v[60:63], v[218:221], v[160:163], v[60:63]
	v_mfma_f32_16x16x32_bf16 v[52:55], v[226:229], v[160:163], v[52:55]
	ds_read_b128 v[194:197], v235 offset:0
	v_mfma_f32_16x16x32_bf16 v[44:47], v[218:221], v[168:171], v[44:47]
	ds_read_b128 v[198:201], v235 offset:1024
	v_mfma_f32_16x16x32_bf16 v[36:39], v[226:229], v[168:171], v[36:39]
	ds_read_b128 v[202:205], v235 offset:2048
	s_add_u32 m0, s40, 0x0
	v_mfma_f32_16x16x32_bf16 v[28:31], v[218:221], v[176:179], v[28:31]
	ds_read_b128 v[206:209], v235 offset:3072
	v_mfma_f32_16x16x32_bf16 v[20:23], v[226:229], v[176:179], v[20:23]
	global_load_lds_dwordx4 v236, s[36:37]
	v_mfma_f32_16x16x32_bf16 v[12:15], v[218:221], v[184:187], v[12:15]
	v_mfma_f32_16x16x32_bf16 v[4:7], v[226:229], v[184:187], v[4:7]
	s_add_u32 m0, s40, 0x2000
	v_mfma_f32_16x16x32_bf16 v[60:63], v[222:225], v[164:167], v[60:63]
	v_mfma_f32_16x16x32_bf16 v[52:55], v[230:233], v[164:167], v[52:55]
	global_load_lds_dwordx4 v237, s[36:37]
	v_mfma_f32_16x16x32_bf16 v[44:47], v[222:225], v[172:175], v[44:47]
	v_mfma_f32_16x16x32_bf16 v[36:39], v[230:233], v[172:175], v[36:39]
	s_add_u32 s36, s36, 0x80
	s_addc_u32 s37, s37, 0
	v_mfma_f32_16x16x32_bf16 v[28:31], v[222:225], v[180:183], v[28:31]
	v_mfma_f32_16x16x32_bf16 v[20:23], v[230:233], v[180:183], v[20:23]
	v_mfma_f32_16x16x32_bf16 v[12:15], v[222:225], v[188:191], v[12:15]
	v_mfma_f32_16x16x32_bf16 v[4:7], v[230:233], v[188:191], v[4:7]
	s_add_i32 s41, s41, -1

; #define STAGE(P, BASE, br, kt) do { const u16* _gb = (BASE) + ((size_t)(br) * K + (size_t)(kt) * BK); \
;     __builtin_amdgcn_global_load_lds((const unsigned*)(_gb + goff0), (unsigned*)((char*)(P) + tid * 16), 16, 0, 0); \
;     __builtin_amdgcn_global_load_lds((const unsigned*)(_gb + (size_t)64 * K + goff0), (unsigned*)((char*)(P) + tid * 16 + 8192), 16, 0, 0); } while (0)
; #define LDA(dst, b, h) _Pragma("unroll") for (int m = 0; m < 4; ++m) _Pragma("unroll") for (int k = 0; k < 2; ++k) \
;     dst[m][k] = *reinterpret_cast<const bf16x8*>((char*)SA(b, h) + lds_byte(wr * 64 + m * 16 + fr, k * 32 + fq * 8))
; #define LDB(dst, b, h) _Pragma("unroll") for (int n = 0; n < 2; ++n) _Pragma("unroll") for (int k = 0; k < 2; ++k) \
;     dst[n][k] = *reinterpret_cast<const bf16x8*>((char*)SB(b, h) + lds_byte(wc * 32 + n * 16 + fr, k * 32 + fq * 8))
; #define MMA(ai, bj, At, Bt_) do { __builtin_amdgcn_s_setprio(1); \
;     _Pragma("unroll") for (int m = 0; m < 4; ++m) _Pragma("unroll") for (int n = 0; n < 2; ++n) _Pragma("unroll") for (int k = 0; k < 2; ++k) \
;       acc[ai][bj][m][n] = __builtin_amdgcn_mfma_f32_16x16x32_bf16(Bt_[n][k], At[m][k], acc[ai][bj][m][n], 0, 0, 0); \
;     __builtin_amdgcn_s_setprio(0); } while (0)
; #define WAIT_V(n) asm volatile("s_waitcnt vmcnt(" #n ")" ::: "memory")
; #define WAIT_L(n) asm volatile("s_waitcnt lgkmcnt(" #n ")" ::: "memory")
; #define BAR __builtin_amdgcn_s_barrier()
; __device__ __forceinline__ void gemm_phase(KP p, char* shmc, const u16* __restrict__ A,
;                                            const u16* __restrict__ Bt, const int N, const int K, const int mode,
;                                            const float* __restrict__ xin, const float resw) {
;     ...
;     for (int t = 0; t < nt - 2; t += 2) {
;       LDB(B0, 0, 0); SCHED; LDA(At, 0, 0); STAGE(SA(1, 1), A, brow + HALF, t + 1);
;       WAIT_L(8); BAR; WAIT_L(0); MMA(0, 0, At, B0); BAR; SCHED;
;       LDB(B1, 0, 1); STAGE(SB(0, 0), Bt, bcol, t + 2);
;       BAR; WAIT_L(0); MMA(0, 1, At, B1); BAR;
;       LDA(At, 0, 1); STAGE(SA(0, 0), A, brow, t + 2);
;       BAR; WAIT_L(0); MMA(1, 0, At, B0); BAR; SCHED;
;       STAGE(SB(0, 1), Bt, bcol + HALF, t + 2);
;       WAIT_V(6); BAR; MMA(1, 1, At, B1); BAR;
;       LDB(B0, 1, 0); SCHED; LDA(At, 1, 0); STAGE(SA(0, 1), A, brow + HALF, t + 2);
;       WAIT_L(8); BAR; WAIT_L(0); MMA(0, 0, At, B0); BAR; SCHED;
.Lmy_entry_sw:
	s_waitcnt vmcnt(12) lgkmcnt(0)
	s_barrier
	v_mfma_f32_16x16x32_bf16 v[120:123], v[128:131], v[194:197], 0
	v_mfma_f32_16x16x32_bf16 v[112:115], v[128:131], v[202:205], 0
	ds_read_b128 v[218:221], v235 offset:16384
	v_mfma_f32_16x16x32_bf16 v[104:107], v[136:139], v[194:197], 0
	ds_read_b128 v[222:225], v235 offset:17408
	s_add_u32 m0, s40, 0x0
	v_mfma_f32_16x16x32_bf16 v[96:99], v[136:139], v[202:205], 0
	ds_read_b128 v[226:229], v235 offset:18432
	global_load_lds_dwordx4 v236, s[36:37]
	v_mfma_f32_16x16x32_bf16 v[88:91], v[144:147], v[194:197], 0
	ds_read_b128 v[230:233], v235 offset:19456
	s_add_u32 m0, s40, 0x2000
	v_mfma_f32_16x16x32_bf16 v[80:83], v[144:147], v[202:205], 0
	global_load_lds_dwordx4 v237, s[36:37]
	v_mfma_f32_16x16x32_bf16 v[72:75], v[152:155], v[194:197], 0
	s_add_u32 s36, s36, 0x80
	s_addc_u32 s37, s37, 0
	v_mfma_f32_16x16x32_bf16 v[64:67], v[152:155], v[202:205], 0
	s_add_u32 m0, s40, 0x10000
	v_mfma_f32_16x16x32_bf16 v[120:123], v[132:135], v[198:201], v[120:123]
	global_load_lds_dwordx4 v236, s[26:27]
	v_mfma_f32_16x16x32_bf16 v[112:115], v[132:135], v[206:209], v[112:115]
	s_add_u32 m0, s40, 0x12000
	v_mfma_f32_16x16x32_bf16 v[104:107], v[140:143], v[198:201], v[104:107]
	global_load_lds_dwordx4 v237, s[26:27]
	v_mfma_f32_16x16x32_bf16 v[96:99], v[140:143], v[206:209], v[96:99]
	s_add_u32 s26, s26, 0x80
	s_addc_u32 s27, s27, 0
	v_mfma_f32_16x16x32_bf16 v[88:91], v[148:151], v[198:201], v[88:91]
	v_mfma_f32_16x16x32_bf16 v[80:83], v[148:151], v[206:209], v[80:83]
	v_mfma_f32_16x16x32_bf16 v[72:75], v[156:159], v[198:201], v[72:75]
	v_mfma_f32_16x16x32_bf16 v[64:67], v[156:159], v[206:209], v[64:67]
	s_waitcnt vmcnt(12) lgkmcnt(0)
	s_barrier
	v_mfma_f32_16x16x32_bf16 v[124:127], v[128:131], v[218:221], 0
	v_mfma_f32_16x16x32_bf16 v[116:119], v[128:131], v[226:229], 0
	ds_read_b128 v[160:163], v234 offset:16384
	v_mfma_f32_16x16x32_bf16 v[108:111], v[136:139], v[218:221], 0
	ds_read_b128 v[164:167], v234 offset:17408
	v_mfma_f32_16x16x32_bf16 v[100:103], v[136:139], v[226:229], 0
	ds_read_b128 v[168:171], v234 offset:18432
	s_add_u32 m0, s40, 0x14000
	v_mfma_f32_16x16x32_bf16 v[92:95], v[144:147], v[218:221], 0
	ds_read_b128 v[172:175], v234 offset:19456
	v_mfma_f32_16x16x32_bf16 v[84:87], v[144:147], v[226:229], 0
	ds_read_b128 v[176:179], v234 offset:20480
	global_load_lds_dwordx4 v236, s[38:39]
	v_mfma_f32_16x16x32_bf16 v[76:79], v[152:155], v[218:221], 0
	ds_read_b128 v[180:183], v234 offset:21504
	v_mfma_f32_16x16x32_bf16 v[68:71], v[152:155], v[226:229], 0
	ds_read_b128 v[184:187], v234 offset:22528
	s_add_u32 m0, s40, 0x16000
	v_mfma_f32_16x16x32_bf16 v[124:127], v[132:135], v[222:225], v[124:127]
	ds_read_b128 v[188:191], v234 offset:23552
	v_mfma_f32_16x16x32_bf16 v[116:119], v[132:135], v[230:233], v[116:119]
	global_load_lds_dwordx4 v237, s[38:39]
	v_mfma_f32_16x16x32_bf16 v[108:111], v[140:143], v[222:225], v[108:111]
	v_mfma_f32_16x16x32_bf16 v[100:103], v[140:143], v[230:233], v[100:103]
	s_add_u32 s38, s38, 0x80
	s_addc_u32 s39, s39, 0
	v_mfma_f32_16x16x32_bf16 v[92:95], v[148:151], v[222:225], v[92:95]
	v_mfma_f32_16x16x32_bf16 v[84:87], v[148:151], v[230:233], v[84:87]
	v_mfma_f32_16x16x32_bf16 v[76:79], v[156:159], v[222:225], v[76:79]
	v_mfma_f32_16x16x32_bf16 v[68:71], v[156:159], v[230:233], v[68:71]
	s_waitcnt vmcnt(12) lgkmcnt(0)
	s_barrier
	v_mfma_f32_16x16x32_bf16 v[56:59], v[160:163], v[194:197], 0
	v_mfma_f32_16x16x32_bf16 v[48:51], v[160:163], v[202:205], 0
	ds_read_b128 v[128:131], v234 offset:32768
	v_mfma_f32_16x16x32_bf16 v[40:43], v[168:171], v[194:197], 0
	ds_read_b128 v[132:135], v234 offset:33792
	v_mfma_f32_16x16x32_bf16 v[32:35], v[168:171], v[202:205], 0
	ds_read_b128 v[136:139], v234 offset:34816
	s_add_u32 m0, s40, 0x4000
	v_mfma_f32_16x16x32_bf16 v[24:27], v[176:179], v[194:197], 0
	ds_read_b128 v[140:143], v234 offset:35840
	v_mfma_f32_16x16x32_bf16 v[16:19], v[176:179], v[202:205], 0
	ds_read_b128 v[144:147], v234 offset:36864
	global_load_lds_dwordx4 v236, s[8:9]
	v_mfma_f32_16x16x32_bf16 v[8:11], v[184:187], v[194:197], 0
	ds_read_b128 v[148:151], v234 offset:37888
	v_mfma_f32_16x16x32_bf16 v[0:3], v[184:187], v[202:205], 0
	ds_read_b128 v[152:155], v234 offset:38912
	s_add_u32 m0, s40, 0x6000
	v_mfma_f32_16x16x32_bf16 v[56:59], v[164:167], v[198:201], v[56:59]
	ds_read_b128 v[156:159], v234 offset:39936
	v_mfma_f32_16x16x32_bf16 v[48:51], v[164:167], v[206:209], v[48:51]
	global_load_lds_dwordx4 v237, s[8:9]
	v_mfma_f32_16x16x32_bf16 v[40:43], v[172:175], v[198:201], v[40:43]
	v_mfma_f32_16x16x32_bf16 v[32:35], v[172:175], v[206:209], v[32:35]
	s_add_u32 s8, s8, 0x80
	s_addc_u32 s9, s9, 0
	v_mfma_f32_16x16x32_bf16 v[24:27], v[180:183], v[198:201], v[24:27]
	v_mfma_f32_16x16x32_bf16 v[16:19], v[180:183], v[206:209], v[16:19]
	v_mfma_f32_16x16x32_bf16 v[8:11], v[188:191], v[198:201], v[8:11]
	v_mfma_f32_16x16x32_bf16 v[0:3], v[188:191], v[206:209], v[0:3]
	s_waitcnt vmcnt(12) lgkmcnt(0)
	s_barrier
; #define STAGE(P, BASE, br, kt) do { const u16* _gb = (BASE) + ((size_t)(br) * K + (size_t)(kt) * BK); \
;     __builtin_amdgcn_global_load_lds((const unsigned*)(_gb + goff0), (unsigned*)((char*)(P) + tid * 16), 16, 0, 0); \
;     __builtin_amdgcn_global_load_lds((const unsigned*)(_gb + (size_t)64 * K + goff0), (unsigned*)((char*)(P) + tid * 16 + 8192), 16, 0, 0); } while (0)
; #define LDA(dst, b, h) _Pragma("unroll") for (int m = 0; m < 4; ++m) _Pragma("unroll") for (int k = 0; k < 2; ++k) \
;     dst[m][k] = *reinterpret_cast<const bf16x8*>((char*)SA(b, h) + lds_byte(wr * 64 + m * 16 + fr, k * 32 + fq * 8))
; #define LDB(dst, b, h) _Pragma("unroll") for (int n = 0; n < 2; ++n) _Pragma("unroll") for (int k = 0; k < 2; ++k) \
;     dst[n][k] = *reinterpret_cast<const bf16x8*>((char*)SB(b, h) + lds_byte(wc * 32 + n * 16 + fr, k * 32 + fq * 8))
; #define WAIT_V(n) asm volatile("s_waitcnt vmcnt(" #n ")" ::: "memory")
; #define WAIT_L(n) asm volatile("s_waitcnt lgkmcnt(" #n ")" ::: "memory")
; #define BAR __builtin_amdgcn_s_barrier()
; #define SCHED __builtin_amdgcn_sched_barrier(0)
; __device__ __forceinline__ void gemm_phase(KP p, char* shmc, const u16* __restrict__ A,
;                                            const u16* __restrict__ Bt, const int N, const int K, const int mode,
;                                            const float* __restrict__ xin, const float resw) {
;     ...
;     for (int t = 0; t < nt - 2; t += 2) {
;       LDB(B0, 0, 0); SCHED; LDA(At, 0, 0); STAGE(SA(1, 1), A, brow + HALF, t + 1);
;       WAIT_L(8); BAR; WAIT_L(0); MMA(0, 0, At, B0); BAR; SCHED;
;       LDB(B1, 0, 1); STAGE(SB(0, 0), Bt, bcol, t + 2);
;       BAR; WAIT_L(0); MMA(0, 1, At, B1); BAR;
;       LDA(At, 0, 1); STAGE(SA(0, 0), A, brow, t + 2);
;       BAR; WAIT_L(0); MMA(1, 0, At, B0); BAR; SCHED;
;       STAGE(SB(0, 1), Bt, bcol + HALF, t + 2);
;       WAIT_V(6); BAR; MMA(1, 1, At, B1); BAR;
;       LDB(B0, 1, 0); SCHED; LDA(At, 1, 0); STAGE(SA(0, 1), A, brow + HALF, t + 2);
;       WAIT_L(8); BAR; WAIT_L(0); MMA(0, 0, At, B0); BAR; SCHED;
;       LDB(B1, 1, 1); STAGE(SB(1, 0), Bt, bcol, t + 3);
;       BAR; WAIT_L(0); MMA(0, 1, At, B1); BAR;
;       LDA(At, 1, 1); STAGE(SA(1, 0), A, brow, t + 3);
;       BAR; WAIT_L(0); MMA(1, 0, At, B0); BAR; SCHED;
;       STAGE(SB(1, 1), Bt, bcol + HALF, t + 3);
;       WAIT_V(6); BAR; MMA(1, 1, At, B1); BAR;
;     }
	v_mfma_f32_16x16x32_bf16 v[60:63], v[160:163], v[218:221], 0
	v_mfma_f32_16x16x32_bf16 v[52:55], v[160:163], v[226:229], 0
	ds_read_b128 v[194:197], v235 offset:32768
	v_mfma_f32_16x16x32_bf16 v[44:47], v[168:171], v[218:221], 0
	ds_read_b128 v[198:201], v235 offset:33792
	v_mfma_f32_16x16x32_bf16 v[36:39], v[168:171], v[226:229], 0
	ds_read_b128 v[202:205], v235 offset:34816
	s_add_u32 m0, s40, 0x8000
	v_mfma_f32_16x16x32_bf16 v[28:31], v[176:179], v[218:221], 0
	ds_read_b128 v[206:209], v235 offset:35840
	v_mfma_f32_16x16x32_bf16 v[20:23], v[176:179], v[226:229], 0
	global_load_lds_dwordx4 v236, s[36:37]
	v_mfma_f32_16x16x32_bf16 v[12:15], v[184:187], v[218:221], 0
	v_mfma_f32_16x16x32_bf16 v[4:7], v[184:187], v[226:229], 0
	s_add_u32 m0, s40, 0xa000
	v_mfma_f32_16x16x32_bf16 v[60:63], v[164:167], v[222:225], v[60:63]
	v_mfma_f32_16x16x32_bf16 v[52:55], v[164:167], v[230:233], v[52:55]
	global_load_lds_dwordx4 v237, s[36:37]
	v_mfma_f32_16x16x32_bf16 v[44:47], v[172:175], v[222:225], v[44:47]
	v_mfma_f32_16x16x32_bf16 v[36:39], v[172:175], v[230:233], v[36:39]
	s_add_u32 s36, s36, 0x80
	s_addc_u32 s37, s37, 0
	v_mfma_f32_16x16x32_bf16 v[28:31], v[180:183], v[222:225], v[28:31]
	v_mfma_f32_16x16x32_bf16 v[20:23], v[180:183], v[230:233], v[20:23]
	v_mfma_f32_16x16x32_bf16 v[12:15], v[188:191], v[222:225], v[12:15]
	v_mfma_f32_16x16x32_bf16 v[4:7], v[188:191], v[230:233], v[4:7]
	s_waitcnt vmcnt(12) lgkmcnt(0)
	s_barrier
	v_mfma_f32_16x16x32_bf16 v[120:123], v[128:131], v[194:197], v[120:123]
	v_mfma_f32_16x16x32_bf16 v[112:115], v[128:131], v[202:205], v[112:115]
	ds_read_b128 v[218:221], v235 offset:49152
	v_mfma_f32_16x16x32_bf16 v[104:107], v[136:139], v[194:197], v[104:107]
	ds_read_b128 v[222:225], v235 offset:50176
	v_mfma_f32_16x16x32_bf16 v[96:99], v[136:139], v[202:205], v[96:99]
	ds_read_b128 v[226:229], v235 offset:51200
	s_add_u32 m0, s40, 0x18000
	v_mfma_f32_16x16x32_bf16 v[88:91], v[144:147], v[194:197], v[88:91]
	ds_read_b128 v[230:233], v235 offset:52224
	v_mfma_f32_16x16x32_bf16 v[80:83], v[144:147], v[202:205], v[80:83]
	global_load_lds_dwordx4 v236, s[26:27]
	v_mfma_f32_16x16x32_bf16 v[72:75], v[152:155], v[194:197], v[72:75]
	v_mfma_f32_16x16x32_bf16 v[64:67], v[152:155], v[202:205], v[64:67]
	s_add_u32 m0, s40, 0x1a000
	v_mfma_f32_16x16x32_bf16 v[120:123], v[132:135], v[198:201], v[120:123]
	v_mfma_f32_16x16x32_bf16 v[112:115], v[132:135], v[206:209], v[112:115]
	global_load_lds_dwordx4 v237, s[26:27]
	v_mfma_f32_16x16x32_bf16 v[104:107], v[140:143], v[198:201], v[104:107]
	v_mfma_f32_16x16x32_bf16 v[96:99], v[140:143], v[206:209], v[96:99]
	s_add_u32 s26, s26, 0x80
	s_addc_u32 s27, s27, 0
	v_mfma_f32_16x16x32_bf16 v[88:91], v[148:151], v[198:201], v[88:91]
	v_mfma_f32_16x16x32_bf16 v[80:83], v[148:151], v[206:209], v[80:83]
	v_mfma_f32_16x16x32_bf16 v[72:75], v[156:159], v[198:201], v[72:75]
	v_mfma_f32_16x16x32_bf16 v[64:67], v[156:159], v[206:209], v[64:67]
	s_waitcnt vmcnt(12) lgkmcnt(0)
	s_barrier
	v_mfma_f32_16x16x32_bf16 v[124:127], v[128:131], v[218:221], v[124:127]
	v_mfma_f32_16x16x32_bf16 v[116:119], v[128:131], v[226:229], v[116:119]
	ds_read_b128 v[160:163], v234 offset:49152
	v_mfma_f32_16x16x32_bf16 v[108:111], v[136:139], v[218:221], v[108:111]
	ds_read_b128 v[164:167], v234 offset:50176
	v_mfma_f32_16x16x32_bf16 v[100:103], v[136:139], v[226:229], v[100:103]
	ds_read_b128 v[168:171], v234 offset:51200
	s_add_u32 m0, s40, 0x1c000
	v_mfma_f32_16x16x32_bf16 v[92:95], v[144:147], v[218:221], v[92:95]
	ds_read_b128 v[172:175], v234 offset:52224
	v_mfma_f32_16x16x32_bf16 v[84:87], v[144:147], v[226:229], v[84:87]
	ds_read_b128 v[176:179], v234 offset:53248
	global_load_lds_dwordx4 v236, s[38:39]
	v_mfma_f32_16x16x32_bf16 v[76:79], v[152:155], v[218:221], v[76:79]
	ds_read_b128 v[180:183], v234 offset:54272
	v_mfma_f32_16x16x32_bf16 v[68:71], v[152:155], v[226:229], v[68:71]
	ds_read_b128 v[184:187], v234 offset:55296
	s_add_u32 m0, s40, 0x1e000
	v_mfma_f32_16x16x32_bf16 v[124:127], v[132:135], v[222:225], v[124:127]
	ds_read_b128 v[188:191], v234 offset:56320
	v_mfma_f32_16x16x32_bf16 v[116:119], v[132:135], v[230:233], v[116:119]
	global_load_lds_dwordx4 v237, s[38:39]
	v_mfma_f32_16x16x32_bf16 v[108:111], v[140:143], v[222:225], v[108:111]
	v_mfma_f32_16x16x32_bf16 v[100:103], v[140:143], v[230:233], v[100:103]
	s_add_u32 s38, s38, 0x80
	s_addc_u32 s39, s39, 0
	v_mfma_f32_16x16x32_bf16 v[92:95], v[148:151], v[222:225], v[92:95]
	v_mfma_f32_16x16x32_bf16 v[84:87], v[148:151], v[230:233], v[84:87]
	v_mfma_f32_16x16x32_bf16 v[76:79], v[156:159], v[222:225], v[76:79]
	v_mfma_f32_16x16x32_bf16 v[68:71], v[156:159], v[230:233], v[68:71]
	s_waitcnt vmcnt(12) lgkmcnt(0)
	s_barrier
; #define STAGE(P, BASE, br, kt) do { const u16* _gb = (BASE) + ((size_t)(br) * K + (size_t)(kt) * BK); \
;     __builtin_amdgcn_global_load_lds((const unsigned*)(_gb + goff0), (unsigned*)((char*)(P) + tid * 16), 16, 0, 0); \
;     __builtin_amdgcn_global_load_lds((const unsigned*)(_gb + (size_t)64 * K + goff0), (unsigned*)((char*)(P) + tid * 16 + 8192), 16, 0, 0); } while (0)
; #define LDA(dst, b, h) _Pragma("unroll") for (int m = 0; m < 4; ++m) _Pragma("unroll") for (int k = 0; k < 2; ++k) \
;     dst[m][k] = *reinterpret_cast<const bf16x8*>((char*)SA(b, h) + lds_byte(wr * 64 + m * 16 + fr, k * 32 + fq * 8))
; #define LDB(dst, b, h) _Pragma("unroll") for (int n = 0; n < 2; ++n) _Pragma("unroll") for (int k = 0; k < 2; ++k) \
;     dst[n][k] = *reinterpret_cast<const bf16x8*>((char*)SB(b, h) + lds_byte(wc * 32 + n * 16 + fr, k * 32 + fq * 8))
; #define WAIT_V(n) asm volatile("s_waitcnt vmcnt(" #n ")" ::: "memory")
; #define WAIT_L(n) asm volatile("s_waitcnt lgkmcnt(" #n ")" ::: "memory")
; #define BAR __builtin_amdgcn_s_barrier()
; #define SCHED __builtin_amdgcn_sched_barrier(0)
; __device__ __forceinline__ void gemm_phase(KP p, char* shmc, const u16* __restrict__ A,
;                                            const u16* __restrict__ Bt, const int N, const int K, const int mode,
;                                            const float* __restrict__ xin, const float resw) {
;     ...
;     for (int t = 0; t < nt - 2; t += 2) {
;       LDB(B0, 0, 0); SCHED; LDA(At, 0, 0); STAGE(SA(1, 1), A, brow + HALF, t + 1);
;       WAIT_L(8); BAR; WAIT_L(0); MMA(0, 0, At, B0); BAR; SCHED;
;       LDB(B1, 0, 1); STAGE(SB(0, 0), Bt, bcol, t + 2);
;       BAR; WAIT_L(0); MMA(0, 1, At, B1); BAR;
;       LDA(At, 0, 1); STAGE(SA(0, 0), A, brow, t + 2);
;       BAR; WAIT_L(0); MMA(1, 0, At, B0); BAR; SCHED;
;       STAGE(SB(0, 1), Bt, bcol + HALF, t + 2);
;       WAIT_V(6); BAR; MMA(1, 1, At, B1); BAR;
;       LDB(B0, 1, 0); SCHED; LDA(At, 1, 0); STAGE(SA(0, 1), A, brow + HALF, t + 2);
;       WAIT_L(8); BAR; WAIT_L(0); MMA(0, 0, At, B0); BAR; SCHED;
;       LDB(B1, 1, 1); STAGE(SB(1, 0), Bt, bcol, t + 3);
;       BAR; WAIT_L(0); MMA(0, 1, At, B1); BAR;
;       LDA(At, 1, 1); STAGE(SA(1, 0), A, brow, t + 3);
;       BAR; WAIT_L(0); MMA(1, 0, At, B0); BAR; SCHED;
;       STAGE(SB(1, 1), Bt, bcol + HALF, t + 3);
;       WAIT_V(6); BAR; MMA(1, 1, At, B1); BAR;
;     }
	v_mfma_f32_16x16x32_bf16 v[56:59], v[160:163], v[194:197], v[56:59]
	v_mfma_f32_16x16x32_bf16 v[48:51], v[160:163], v[202:205], v[48:51]
	ds_read_b128 v[128:131], v234 offset:0
	v_mfma_f32_16x16x32_bf16 v[40:43], v[168:171], v[194:197], v[40:43]
	ds_read_b128 v[132:135], v234 offset:1024
	v_mfma_f32_16x16x32_bf16 v[32:35], v[168:171], v[202:205], v[32:35]
	ds_read_b128 v[136:139], v234 offset:2048
	s_add_u32 m0, s40, 0xc000
	v_mfma_f32_16x16x32_bf16 v[24:27], v[176:179], v[194:197], v[24:27]
	ds_read_b128 v[140:143], v234 offset:3072
	v_mfma_f32_16x16x32_bf16 v[16:19], v[176:179], v[202:205], v[16:19]
	ds_read_b128 v[144:147], v234 offset:4096
	global_load_lds_dwordx4 v236, s[8:9]
	v_mfma_f32_16x16x32_bf16 v[8:11], v[184:187], v[194:197], v[8:11]
	ds_read_b128 v[148:151], v234 offset:5120
	v_mfma_f32_16x16x32_bf16 v[0:3], v[184:187], v[202:205], v[0:3]
	ds_read_b128 v[152:155], v234 offset:6144
	s_add_u32 m0, s40, 0xe000
	v_mfma_f32_16x16x32_bf16 v[56:59], v[164:167], v[198:201], v[56:59]
	ds_read_b128 v[156:159], v234 offset:7168
	v_mfma_f32_16x16x32_bf16 v[48:51], v[164:167], v[206:209], v[48:51]
	global_load_lds_dwordx4 v237, s[8:9]
	v_mfma_f32_16x16x32_bf16 v[40:43], v[172:175], v[198:201], v[40:43]
	v_mfma_f32_16x16x32_bf16 v[32:35], v[172:175], v[206:209], v[32:35]
	s_add_u32 s8, s8, 0x80
	s_addc_u32 s9, s9, 0
	v_mfma_f32_16x16x32_bf16 v[24:27], v[180:183], v[198:201], v[24:27]
	v_mfma_f32_16x16x32_bf16 v[16:19], v[180:183], v[206:209], v[16:19]
	v_mfma_f32_16x16x32_bf16 v[8:11], v[188:191], v[198:201], v[8:11]
	v_mfma_f32_16x16x32_bf16 v[0:3], v[188:191], v[206:209], v[0:3]
	s_waitcnt vmcnt(12) lgkmcnt(0)
	s_barrier
	v_mfma_f32_16x16x32_bf16 v[60:63], v[160:163], v[218:221], v[60:63]
	v_mfma_f32_16x16x32_bf16 v[52:55], v[160:163], v[226:229], v[52:55]
	ds_read_b128 v[194:197], v235 offset:0
	v_mfma_f32_16x16x32_bf16 v[44:47], v[168:171], v[218:221], v[44:47]
	ds_read_b128 v[198:201], v235 offset:1024
	v_mfma_f32_16x16x32_bf16 v[36:39], v[168:171], v[226:229], v[36:39]
	ds_read_b128 v[202:205], v235 offset:2048
	s_add_u32 m0, s40, 0x0
	v_mfma_f32_16x16x32_bf16 v[28:31], v[176:179], v[218:221], v[28:31]
	ds_read_b128 v[206:209], v235 offset:3072
	v_mfma_f32_16x16x32_bf16 v[20:23], v[176:179], v[226:229], v[20:23]
	global_load_lds_dwordx4 v236, s[36:37]
	v_mfma_f32_16x16x32_bf16 v[12:15], v[184:187], v[218:221], v[12:15]
	v_mfma_f32_16x16x32_bf16 v[4:7], v[184:187], v[226:229], v[4:7]
	s_add_u32 m0, s40, 0x2000
	v_mfma_f32_16x16x32_bf16 v[60:63], v[164:167], v[222:225], v[60:63]
	v_mfma_f32_16x16x32_bf16 v[52:55], v[164:167], v[230:233], v[52:55]
	global_load_lds_dwordx4 v237, s[36:37]
	v_mfma_f32_16x16x32_bf16 v[44:47], v[172:175], v[222:225], v[44:47]
	v_mfma_f32_16x16x32_bf16 v[36:39], v[172:175], v[230:233], v[36:39]
	s_add_u32 s36, s36, 0x80
	s_addc_u32 s37, s37, 0
	v_mfma_f32_16x16x32_bf16 v[28:31], v[180:183], v[222:225], v[28:31]
	v_mfma_f32_16x16x32_bf16 v[20:23], v[180:183], v[230:233], v[20:23]
	v_mfma_f32_16x16x32_bf16 v[12:15], v[188:191], v[222:225], v[12:15]
	v_mfma_f32_16x16x32_bf16 v[4:7], v[188:191], v[230:233], v[4:7]
	s_add_i32 s41, s41, -1
